# grid barrier release: non-leader workgroups poll the top generation word directly instead of the per-XCD generation word (one release hop fewer)
# speedup vs baseline: 1.0075x; 1.0075x over previous
.LBB0_175:
	s_lshl_b32 s22, s33, 6
	s_add_i32 s4, s22, 0x500
	s_mov_b32 s5, 0
	s_lshl_b64 s[0:1], s[4:5], 2
	s_add_u32 s0, s34, s0
	s_addc_u32 s1, s35, s1
	v_mov_b32_e32 v1, 1
	v_mov_b64_e32 v[6:7], s[0:1]
	flat_atomic_add v1, v[6:7], v1 sc0
	v_cvt_f32_u32_e32 v3, v4
	v_sub_u32_e32 v5, 0, v4
	v_rcp_iflag_f32_e32 v3, v3
	s_nop 0
	v_mul_f32_e32 v3, 0x4f7ffffe, v3
	v_cvt_u32_f32_e32 v3, v3
	v_mul_lo_u32 v5, v5, v3
	v_mul_hi_u32 v5, v3, v5
	v_add_u32_e32 v3, v3, v5
	s_waitcnt vmcnt(0) lgkmcnt(0)
	v_mul_hi_u32 v3, v1, v3
	v_mul_lo_u32 v5, v3, v4
	v_add_u32_e32 v6, 1, v1
	v_sub_u32_e32 v1, v1, v5
	v_add_u32_e32 v7, 1, v3
	v_cmp_ge_u32_e32 vcc, v1, v4
	v_sub_u32_e32 v5, v1, v4
	s_nop 0
	v_cndmask_b32_e32 v3, v3, v7, vcc
	v_cndmask_b32_e32 v1, v1, v5, vcc
	v_add_u32_e32 v5, 1, v3
	v_cmp_ge_u32_e32 vcc, v1, v4
	s_nop 1
	v_cndmask_b32_e32 v1, v3, v5, vcc
	v_mad_u64_u32 v[4:5], s[0:1], v4, v1, v[4:5]
	v_cmp_ne_u32_e32 vcc, v6, v4
	s_and_saveexec_b64 s[0:1], vcc
	s_xor_b64 s[0:1], exec, s[0:1]
	s_cbranch_execz .LBB0_188
	s_movk_i32 s4, 0xd40
	s_lshl_b64 s[4:5], s[4:5], 2
	s_add_u32 s6, s34, s4
	s_addc_u32 s7, s35, s5
	v_mov_b64_e32 v[2:3], s[6:7]
	flat_load_dword v2, v[2:3] sc1
	s_waitcnt vmcnt(0) lgkmcnt(0)
	v_cmp_eq_u32_e32 vcc, v2, v1
	s_and_saveexec_b64 s[4:5], vcc
	s_cbranch_execz .LBB0_187
	s_mov_b32 s23, 1
	s_mov_b64 s[8:9], 0
	s_branch .LBB0_179

.LBB0_526:
	s_lshl_b32 s22, s38, 6
	s_add_i32 s64, s22, 0x500
	s_lshl_b64 s[0:1], s[64:65], 2
	s_add_u32 s0, s36, s0
	s_addc_u32 s1, s37, s1
	v_mov_b64_e32 v[6:7], s[0:1]
	flat_atomic_add v5, v[6:7], v227 sc0
	v_cvt_f32_u32_e32 v1, v4
	v_sub_u32_e32 v6, 0, v4
	v_rcp_iflag_f32_e32 v1, v1
	s_nop 0
	v_mul_f32_e32 v1, 0x4f7ffffe, v1
	v_cvt_u32_f32_e32 v1, v1
	v_mul_lo_u32 v6, v6, v1
	v_mul_hi_u32 v6, v1, v6
	v_add_u32_e32 v1, v1, v6
	s_waitcnt vmcnt(0) lgkmcnt(0)
	v_mul_hi_u32 v1, v5, v1
	v_mul_lo_u32 v6, v1, v4
	v_sub_u32_e32 v6, v5, v6
	v_cmp_ge_u32_e32 vcc, v6, v4
	v_add_u32_e32 v7, 1, v1
	s_nop 0
	v_cndmask_b32_e32 v1, v1, v7, vcc
	v_sub_u32_e32 v7, v6, v4
	v_cndmask_b32_e32 v6, v6, v7, vcc
	v_cmp_ge_u32_e32 vcc, v6, v4
	v_add_u32_e32 v6, 1, v1
	s_nop 0
	v_cndmask_b32_e32 v1, v1, v6, vcc
	v_add_u32_e32 v6, 1, v5
	v_mad_u64_u32 v[4:5], s[0:1], v4, v1, v[4:5]
	v_cmp_ne_u32_e32 vcc, v6, v4
	s_and_saveexec_b64 s[0:1], vcc
	s_xor_b64 s[0:1], exec, s[0:1]
	s_cbranch_execz .LBB0_539
	s_movk_i32 s64, 0xd40
	s_lshl_b64 s[4:5], s[64:65], 2
	s_add_u32 s6, s36, s4
	s_addc_u32 s7, s37, s5
	v_mov_b64_e32 v[4:5], s[6:7]
	flat_load_dword v2, v[4:5] sc1
	s_waitcnt vmcnt(0) lgkmcnt(0)
	v_cmp_eq_u32_e32 vcc, v2, v1
	s_and_saveexec_b64 s[4:5], vcc
	s_cbranch_execz .LBB0_538
	s_mov_b32 s23, 1
	s_mov_b64 s[8:9], 0
	s_branch .LBB0_530

.LBB0_586:
	s_lshl_b32 s22, s36, 6
	s_add_i32 s64, s22, 0x500
	s_lshl_b64 s[0:1], s[64:65], 2
	s_add_u32 s0, s34, s0
	s_addc_u32 s1, s35, s1
	v_mov_b64_e32 v[6:7], s[0:1]
	flat_atomic_add v5, v[6:7], v227 sc0
	v_cvt_f32_u32_e32 v1, v4
	v_sub_u32_e32 v6, 0, v4
	v_rcp_iflag_f32_e32 v1, v1
	s_nop 0
	v_mul_f32_e32 v1, 0x4f7ffffe, v1
	v_cvt_u32_f32_e32 v1, v1
	v_mul_lo_u32 v6, v6, v1
	v_mul_hi_u32 v6, v1, v6
	v_add_u32_e32 v1, v1, v6
	s_waitcnt vmcnt(0) lgkmcnt(0)
	v_mul_hi_u32 v1, v5, v1
	v_mul_lo_u32 v6, v1, v4
	v_sub_u32_e32 v6, v5, v6
	v_cmp_ge_u32_e32 vcc, v6, v4
	v_add_u32_e32 v7, 1, v1
	s_nop 0
	v_cndmask_b32_e32 v1, v1, v7, vcc
	v_sub_u32_e32 v7, v6, v4
	v_cndmask_b32_e32 v6, v6, v7, vcc
	v_cmp_ge_u32_e32 vcc, v6, v4
	v_add_u32_e32 v6, 1, v1
	s_nop 0
	v_cndmask_b32_e32 v1, v1, v6, vcc
	v_add_u32_e32 v6, 1, v5
	v_mad_u64_u32 v[4:5], s[0:1], v4, v1, v[4:5]
	v_cmp_ne_u32_e32 vcc, v6, v4
	s_and_saveexec_b64 s[0:1], vcc
	s_xor_b64 s[0:1], exec, s[0:1]
	s_cbranch_execz .LBB0_599
	s_movk_i32 s64, 0xd40
	s_lshl_b64 s[4:5], s[64:65], 2
	s_add_u32 s6, s34, s4
	s_addc_u32 s7, s35, s5
	v_mov_b64_e32 v[4:5], s[6:7]
	flat_load_dword v2, v[4:5] sc1
	s_waitcnt vmcnt(0) lgkmcnt(0)
	v_cmp_eq_u32_e32 vcc, v2, v1
	s_and_saveexec_b64 s[4:5], vcc
	s_cbranch_execz .LBB0_598
	s_mov_b32 s23, 1
	s_mov_b64 s[8:9], 0
	s_branch .LBB0_590

.LBB0_752:
	s_lshl_b32 s20, s39, 6
	s_add_i32 s64, s20, 0x500
	s_lshl_b64 s[0:1], s[64:65], 2
	s_add_u32 s0, s36, s0
	s_addc_u32 s1, s37, s1
	v_mov_b64_e32 v[6:7], s[0:1]
	flat_atomic_add v5, v[6:7], v227 sc0
	v_cvt_f32_u32_e32 v1, v4
	v_sub_u32_e32 v6, 0, v4
	v_rcp_iflag_f32_e32 v1, v1
	s_nop 0
	v_mul_f32_e32 v1, 0x4f7ffffe, v1
	v_cvt_u32_f32_e32 v1, v1
	v_mul_lo_u32 v6, v6, v1
	v_mul_hi_u32 v6, v1, v6
	v_add_u32_e32 v1, v1, v6
	s_waitcnt vmcnt(0) lgkmcnt(0)
	v_mul_hi_u32 v1, v5, v1
	v_mul_lo_u32 v6, v1, v4
	v_sub_u32_e32 v6, v5, v6
	v_cmp_ge_u32_e32 vcc, v6, v4
	v_add_u32_e32 v7, 1, v1
	s_nop 0
	v_cndmask_b32_e32 v1, v1, v7, vcc
	v_sub_u32_e32 v7, v6, v4
	v_cndmask_b32_e32 v6, v6, v7, vcc
	v_cmp_ge_u32_e32 vcc, v6, v4
	v_add_u32_e32 v6, 1, v1
	s_nop 0
	v_cndmask_b32_e32 v1, v1, v6, vcc
	v_add_u32_e32 v6, 1, v5
	v_mad_u64_u32 v[4:5], s[0:1], v4, v1, v[4:5]
	v_cmp_ne_u32_e32 vcc, v6, v4
	s_and_saveexec_b64 s[0:1], vcc
	s_xor_b64 s[0:1], exec, s[0:1]
	s_cbranch_execz .LBB0_765
	s_movk_i32 s64, 0xd40
	s_lshl_b64 s[2:3], s[64:65], 2
	s_add_u32 s4, s36, s2
	s_addc_u32 s5, s37, s3
	v_mov_b64_e32 v[4:5], s[4:5]
	flat_load_dword v2, v[4:5] sc1
	s_waitcnt vmcnt(0) lgkmcnt(0)
	v_cmp_eq_u32_e32 vcc, v2, v1
	s_and_saveexec_b64 s[2:3], vcc
	s_cbranch_execz .LBB0_764
	s_mov_b32 s21, 1
	s_mov_b64 s[6:7], 0
	s_branch .LBB0_756

.LBB0_1227:
	s_lshl_b32 s22, s41, 6
	s_add_i32 s64, s22, 0x500
	s_lshl_b64 s[0:1], s[64:65], 2
	s_add_u32 s0, s38, s0
	s_addc_u32 s1, s39, s1
	v_mov_b64_e32 v[6:7], s[0:1]
	flat_atomic_add v5, v[6:7], v227 sc0
	v_cvt_f32_u32_e32 v1, v4
	v_sub_u32_e32 v6, 0, v4
	v_rcp_iflag_f32_e32 v1, v1
	s_nop 0
	v_mul_f32_e32 v1, 0x4f7ffffe, v1
	v_cvt_u32_f32_e32 v1, v1
	v_mul_lo_u32 v6, v6, v1
	v_mul_hi_u32 v6, v1, v6
	v_add_u32_e32 v1, v1, v6
	s_waitcnt vmcnt(0) lgkmcnt(0)
	v_mul_hi_u32 v1, v5, v1
	v_mul_lo_u32 v6, v1, v4
	v_sub_u32_e32 v6, v5, v6
	v_cmp_ge_u32_e32 vcc, v6, v4
	v_add_u32_e32 v7, 1, v1
	s_nop 0
	v_cndmask_b32_e32 v1, v1, v7, vcc
	v_sub_u32_e32 v7, v6, v4
	v_cndmask_b32_e32 v6, v6, v7, vcc
	v_cmp_ge_u32_e32 vcc, v6, v4
	v_add_u32_e32 v6, 1, v1
	s_nop 0
	v_cndmask_b32_e32 v1, v1, v6, vcc
	v_add_u32_e32 v6, 1, v5
	v_mad_u64_u32 v[4:5], s[0:1], v4, v1, v[4:5]
	v_cmp_ne_u32_e32 vcc, v6, v4
	s_and_saveexec_b64 s[0:1], vcc
	s_xor_b64 s[0:1], exec, s[0:1]
	s_cbranch_execz .LBB0_1240
	s_movk_i32 s64, 0xd40
	s_lshl_b64 s[4:5], s[64:65], 2
	s_add_u32 s6, s38, s4
	s_addc_u32 s7, s39, s5
	v_mov_b64_e32 v[4:5], s[6:7]
	flat_load_dword v2, v[4:5] sc1
	s_waitcnt vmcnt(0) lgkmcnt(0)
	v_cmp_eq_u32_e32 vcc, v2, v1
	s_and_saveexec_b64 s[4:5], vcc
	s_cbranch_execz .LBB0_1239
	s_mov_b32 s23, 1
	s_mov_b64 s[8:9], 0
	s_branch .LBB0_1231

.LBB0_1625:
	s_lshl_b32 s20, s38, 6
	s_add_i32 s64, s20, 0x500
	s_lshl_b64 s[0:1], s[64:65], 2
	s_add_u32 s0, s36, s0
	s_addc_u32 s1, s37, s1
	v_mov_b64_e32 v[6:7], s[0:1]
	flat_atomic_add v5, v[6:7], v227 sc0
	v_cvt_f32_u32_e32 v1, v4
	v_sub_u32_e32 v6, 0, v4
	v_rcp_iflag_f32_e32 v1, v1
	s_nop 0
	v_mul_f32_e32 v1, 0x4f7ffffe, v1
	v_cvt_u32_f32_e32 v1, v1
	v_mul_lo_u32 v6, v6, v1
	v_mul_hi_u32 v6, v1, v6
	v_add_u32_e32 v1, v1, v6
	s_waitcnt vmcnt(0) lgkmcnt(0)
	v_mul_hi_u32 v1, v5, v1
	v_mul_lo_u32 v6, v1, v4
	v_sub_u32_e32 v6, v5, v6
	v_cmp_ge_u32_e32 vcc, v6, v4
	v_add_u32_e32 v7, 1, v1
	s_nop 0
	v_cndmask_b32_e32 v1, v1, v7, vcc
	v_sub_u32_e32 v7, v6, v4
	v_cndmask_b32_e32 v6, v6, v7, vcc
	v_cmp_ge_u32_e32 vcc, v6, v4
	v_add_u32_e32 v6, 1, v1
	s_nop 0
	v_cndmask_b32_e32 v1, v1, v6, vcc
	v_add_u32_e32 v6, 1, v5
	v_mad_u64_u32 v[4:5], s[0:1], v4, v1, v[4:5]
	v_cmp_ne_u32_e32 vcc, v6, v4
	s_and_saveexec_b64 s[0:1], vcc
	s_xor_b64 s[0:1], exec, s[0:1]
	s_cbranch_execz .LBB0_1638
	s_movk_i32 s64, 0xd40
	s_lshl_b64 s[2:3], s[64:65], 2
	s_add_u32 s4, s36, s2
	s_addc_u32 s5, s37, s3
	v_mov_b64_e32 v[4:5], s[4:5]
	flat_load_dword v2, v[4:5] sc1
	s_waitcnt vmcnt(0) lgkmcnt(0)
	v_cmp_eq_u32_e32 vcc, v2, v1
	s_and_saveexec_b64 s[2:3], vcc
	s_cbranch_execz .LBB0_1637
	s_mov_b32 s21, 1
	s_mov_b64 s[6:7], 0
	s_branch .LBB0_1629

.LBB0_1807:
	s_lshl_b32 s20, s40, 6
	s_add_i32 s64, s20, 0x500
	s_lshl_b64 s[0:1], s[64:65], 2
	s_add_u32 s0, s38, s0
	s_addc_u32 s1, s39, s1
	v_mov_b64_e32 v[6:7], s[0:1]
	flat_atomic_add v5, v[6:7], v227 sc0
	v_cvt_f32_u32_e32 v1, v4
	v_sub_u32_e32 v6, 0, v4
	v_rcp_iflag_f32_e32 v1, v1
	s_nop 0
	v_mul_f32_e32 v1, 0x4f7ffffe, v1
	v_cvt_u32_f32_e32 v1, v1
	v_mul_lo_u32 v6, v6, v1
	v_mul_hi_u32 v6, v1, v6
	v_add_u32_e32 v1, v1, v6
	s_waitcnt vmcnt(0) lgkmcnt(0)
	v_mul_hi_u32 v1, v5, v1
	v_mul_lo_u32 v6, v1, v4
	v_sub_u32_e32 v6, v5, v6
	v_cmp_ge_u32_e32 vcc, v6, v4
	v_add_u32_e32 v7, 1, v1
	s_nop 0
	v_cndmask_b32_e32 v1, v1, v7, vcc
	v_sub_u32_e32 v7, v6, v4
	v_cndmask_b32_e32 v6, v6, v7, vcc
	v_cmp_ge_u32_e32 vcc, v6, v4
	v_add_u32_e32 v6, 1, v1
	s_nop 0
	v_cndmask_b32_e32 v1, v1, v6, vcc
	v_add_u32_e32 v6, 1, v5
	v_mad_u64_u32 v[4:5], s[0:1], v4, v1, v[4:5]
	v_cmp_ne_u32_e32 vcc, v6, v4
	s_and_saveexec_b64 s[0:1], vcc
	s_xor_b64 s[0:1], exec, s[0:1]
	s_cbranch_execz .LBB0_1820
	s_movk_i32 s64, 0xd40
	s_lshl_b64 s[2:3], s[64:65], 2
	s_add_u32 s4, s38, s2
	s_addc_u32 s5, s39, s3
	v_mov_b64_e32 v[4:5], s[4:5]
	flat_load_dword v2, v[4:5] sc1
	s_waitcnt vmcnt(0) lgkmcnt(0)
	v_cmp_eq_u32_e32 vcc, v2, v1
	s_and_saveexec_b64 s[2:3], vcc
	s_cbranch_execz .LBB0_1819
	s_mov_b32 s21, 1
	s_mov_b64 s[6:7], 0
	s_branch .LBB0_1811

.LBB0_1939:
	s_lshl_b32 s20, s36, 6
	s_add_i32 s64, s20, 0x500
	s_lshl_b64 s[0:1], s[64:65], 2
	s_add_u32 s0, s34, s0
	s_addc_u32 s1, s35, s1
	v_mov_b64_e32 v[6:7], s[0:1]
	flat_atomic_add v5, v[6:7], v227 sc0
	v_cvt_f32_u32_e32 v1, v4
	v_sub_u32_e32 v6, 0, v4
	v_rcp_iflag_f32_e32 v1, v1
	s_nop 0
	v_mul_f32_e32 v1, 0x4f7ffffe, v1
	v_cvt_u32_f32_e32 v1, v1
	v_mul_lo_u32 v6, v6, v1
	v_mul_hi_u32 v6, v1, v6
	v_add_u32_e32 v1, v1, v6
	s_waitcnt vmcnt(0) lgkmcnt(0)
	v_mul_hi_u32 v1, v5, v1
	v_mul_lo_u32 v6, v1, v4
	v_sub_u32_e32 v6, v5, v6
	v_cmp_ge_u32_e32 vcc, v6, v4
	v_add_u32_e32 v7, 1, v1
	s_nop 0
	v_cndmask_b32_e32 v1, v1, v7, vcc
	v_sub_u32_e32 v7, v6, v4
	v_cndmask_b32_e32 v6, v6, v7, vcc
	v_cmp_ge_u32_e32 vcc, v6, v4
	v_add_u32_e32 v6, 1, v1
	s_nop 0
	v_cndmask_b32_e32 v1, v1, v6, vcc
	v_add_u32_e32 v6, 1, v5
	v_mad_u64_u32 v[4:5], s[0:1], v4, v1, v[4:5]
	v_cmp_ne_u32_e32 vcc, v6, v4
	s_and_saveexec_b64 s[0:1], vcc
	s_xor_b64 s[0:1], exec, s[0:1]
	s_cbranch_execz .LBB0_1952
	s_movk_i32 s64, 0xd40
	s_lshl_b64 s[2:3], s[64:65], 2
	s_add_u32 s4, s34, s2
	s_addc_u32 s5, s35, s3
	v_mov_b64_e32 v[4:5], s[4:5]
	flat_load_dword v2, v[4:5] sc1
	s_waitcnt vmcnt(0) lgkmcnt(0)
	v_cmp_eq_u32_e32 vcc, v2, v1
	s_and_saveexec_b64 s[2:3], vcc
	s_cbranch_execz .LBB0_1951
	s_mov_b32 s21, 1
	s_mov_b64 s[6:7], 0
	s_branch .LBB0_1943
